# P2c chunk-aggregate scan hand-pipelined too (32 rows in flight, counted vmcnt) on top of pipelined P2d
# baseline (speedup 1.0000x reference)
; __device__ __forceinline__ float bf_lo(unsigned w) { return __uint_as_float(w << 16); }
; __device__ __forceinline__ float bf_hi(unsigned w) { return __uint_as_float(w & 0xffff0000u); }
; __global__ void __launch_bounds__(NTHR, 2) hybrid_block_fwd(Args a) {
;     ...
;         const int c2 = gtid & 1023, chunk = (gtid >> 10) & (NCH - 1), b = gtid >> 16;
;         const size_t r0 = (size_t)b * SEQ + (size_t)chunk * CH_L;
;         const u32x2* pab = (const u32x2*)((const unsigned*)AF + r0 * LW) + c2;
;         f32x2 P = (f32x2){1.f, 1.f}, H = (f32x2){0.f, 0.f};
; #pragma unroll 32
;         for (int i = 0; i < CH_L; ++i) { const u32x2 q = pab[(size_t)i * (LW / 2)];
;             const f32x2 av = (f32x2){__builtin_amdgcn_exp2f(bf_lo(q.x)), __builtin_amdgcn_exp2f(bf_lo(q.y))}, bv = (f32x2){bf_hi(q.x), bf_hi(q.y)}; P = P * av; H = av * H + bv; }
.LBB0_613:
	s_or_b64 exec, exec, s[0:1]
	s_waitcnt lgkmcnt(0)
	v_mov_b32_e32 v0, v212
	v_readlane_b32 s0, v248, 8
	s_barrier
	v_add_u32_e32 v1, s0, v0
	v_and_b32_e32 v1, 0x3ff, v1
	v_lshlrev_b32_e32 v2, 3, v1
	v_add_u32_e32 v6, 0x100000, v2
	s_lshr_b32 s9, s0, 10
	s_lshl_b32 s10, s9, 20
	s_add_u32 s12, s92, s10
	s_addc_u32 s13, s93, 0
	global_load_dwordx2 v[32:33], v2, s[12:13]
	s_add_u32 s12, s12, 0x2000
	s_addc_u32 s13, s13, 0
	global_load_dwordx2 v[34:35], v2, s[12:13]
	s_add_u32 s12, s12, 0x2000
	s_addc_u32 s13, s13, 0
	global_load_dwordx2 v[36:37], v2, s[12:13]
	s_add_u32 s12, s12, 0x2000
	s_addc_u32 s13, s13, 0
	global_load_dwordx2 v[38:39], v2, s[12:13]
	s_add_u32 s12, s12, 0x2000
	s_addc_u32 s13, s13, 0
	global_load_dwordx2 v[40:41], v2, s[12:13]
	s_add_u32 s12, s12, 0x2000
	s_addc_u32 s13, s13, 0
	global_load_dwordx2 v[42:43], v2, s[12:13]
	s_add_u32 s12, s12, 0x2000
	s_addc_u32 s13, s13, 0
	global_load_dwordx2 v[44:45], v2, s[12:13]
	s_add_u32 s12, s12, 0x2000
	s_addc_u32 s13, s13, 0
	global_load_dwordx2 v[46:47], v2, s[12:13]
	s_add_u32 s12, s12, 0x2000
	s_addc_u32 s13, s13, 0
	global_load_dwordx2 v[48:49], v2, s[12:13]
	s_add_u32 s12, s12, 0x2000
	s_addc_u32 s13, s13, 0
	global_load_dwordx2 v[50:51], v2, s[12:13]
	s_add_u32 s12, s12, 0x2000
	s_addc_u32 s13, s13, 0
	global_load_dwordx2 v[52:53], v2, s[12:13]
	s_add_u32 s12, s12, 0x2000
	s_addc_u32 s13, s13, 0
	global_load_dwordx2 v[54:55], v2, s[12:13]
	s_add_u32 s12, s12, 0x2000
	s_addc_u32 s13, s13, 0
	global_load_dwordx2 v[56:57], v2, s[12:13]
	s_add_u32 s12, s12, 0x2000
	s_addc_u32 s13, s13, 0
	global_load_dwordx2 v[58:59], v2, s[12:13]
	s_add_u32 s12, s12, 0x2000
	s_addc_u32 s13, s13, 0
	global_load_dwordx2 v[60:61], v2, s[12:13]
	s_add_u32 s12, s12, 0x2000
	s_addc_u32 s13, s13, 0
	global_load_dwordx2 v[62:63], v2, s[12:13]
	s_add_u32 s12, s12, 0x2000
	s_addc_u32 s13, s13, 0
	global_load_dwordx2 v[64:65], v2, s[12:13]
	s_add_u32 s12, s12, 0x2000
	s_addc_u32 s13, s13, 0
	global_load_dwordx2 v[66:67], v2, s[12:13]
	s_add_u32 s12, s12, 0x2000
	s_addc_u32 s13, s13, 0
	global_load_dwordx2 v[68:69], v2, s[12:13]
	s_add_u32 s12, s12, 0x2000
	s_addc_u32 s13, s13, 0
	global_load_dwordx2 v[70:71], v2, s[12:13]
	s_add_u32 s12, s12, 0x2000
	s_addc_u32 s13, s13, 0
	global_load_dwordx2 v[72:73], v2, s[12:13]
	s_add_u32 s12, s12, 0x2000
	s_addc_u32 s13, s13, 0
	global_load_dwordx2 v[74:75], v2, s[12:13]
	s_add_u32 s12, s12, 0x2000
	s_addc_u32 s13, s13, 0
	global_load_dwordx2 v[76:77], v2, s[12:13]
	s_add_u32 s12, s12, 0x2000
	s_addc_u32 s13, s13, 0
	global_load_dwordx2 v[78:79], v2, s[12:13]
	s_add_u32 s12, s12, 0x2000
	s_addc_u32 s13, s13, 0
	global_load_dwordx2 v[80:81], v2, s[12:13]
	s_add_u32 s12, s12, 0x2000
	s_addc_u32 s13, s13, 0
	global_load_dwordx2 v[82:83], v2, s[12:13]
	s_add_u32 s12, s12, 0x2000
	s_addc_u32 s13, s13, 0
	global_load_dwordx2 v[84:85], v2, s[12:13]
	s_add_u32 s12, s12, 0x2000
	s_addc_u32 s13, s13, 0
	global_load_dwordx2 v[86:87], v2, s[12:13]
	s_add_u32 s12, s12, 0x2000
	s_addc_u32 s13, s13, 0
	global_load_dwordx2 v[88:89], v2, s[12:13]
	s_add_u32 s12, s12, 0x2000
	s_addc_u32 s13, s13, 0
	global_load_dwordx2 v[90:91], v2, s[12:13]
	s_add_u32 s12, s12, 0x2000
	s_addc_u32 s13, s13, 0
	global_load_dwordx2 v[92:93], v2, s[12:13]
	s_add_u32 s12, s12, 0x2000
	s_addc_u32 s13, s13, 0
	global_load_dwordx2 v[94:95], v2, s[12:13]
	s_add_u32 s12, s12, 0x2000
	s_addc_u32 s13, s13, 0
	v_mov_b32_e32 v8, 1.0
	v_mov_b32_e32 v9, 1.0
	v_mov_b32_e32 v10, 0
	v_mov_b32_e32 v11, 0
	s_mov_b32 s8, 3
.Lp2c_steady:
	s_waitcnt vmcnt(31)
	v_lshlrev_b32_e32 v16, 16, v32
	v_lshlrev_b32_e32 v17, 16, v33
	v_exp_f32_e32 v16, v16
	v_exp_f32_e32 v17, v17
	v_and_b32_e32 v18, 0xffff0000, v32
	v_and_b32_e32 v19, 0xffff0000, v33
	global_load_dwordx2 v[32:33], v2, s[12:13]
	s_add_u32 s12, s12, 0x2000
	s_addc_u32 s13, s13, 0
	v_pk_mul_f32 v[8:9], v[8:9], v[16:17]
	v_pk_fma_f32 v[10:11], v[10:11], v[16:17], v[18:19]
	s_waitcnt vmcnt(31)
	v_lshlrev_b32_e32 v24, 16, v34
	v_lshlrev_b32_e32 v25, 16, v35
	v_exp_f32_e32 v24, v24
	v_exp_f32_e32 v25, v25
	v_and_b32_e32 v26, 0xffff0000, v34
	v_and_b32_e32 v27, 0xffff0000, v35
	global_load_dwordx2 v[34:35], v2, s[12:13]
	s_add_u32 s12, s12, 0x2000
	s_addc_u32 s13, s13, 0
	v_pk_mul_f32 v[8:9], v[8:9], v[24:25]
	v_pk_fma_f32 v[10:11], v[10:11], v[24:25], v[26:27]
	s_waitcnt vmcnt(31)
	v_lshlrev_b32_e32 v16, 16, v36
	v_lshlrev_b32_e32 v17, 16, v37
	v_exp_f32_e32 v16, v16
	v_exp_f32_e32 v17, v17
	v_and_b32_e32 v18, 0xffff0000, v36
	v_and_b32_e32 v19, 0xffff0000, v37
	global_load_dwordx2 v[36:37], v2, s[12:13]
	s_add_u32 s12, s12, 0x2000
	s_addc_u32 s13, s13, 0
	v_pk_mul_f32 v[8:9], v[8:9], v[16:17]
	v_pk_fma_f32 v[10:11], v[10:11], v[16:17], v[18:19]
	s_waitcnt vmcnt(31)
	v_lshlrev_b32_e32 v24, 16, v38
	v_lshlrev_b32_e32 v25, 16, v39
	v_exp_f32_e32 v24, v24
	v_exp_f32_e32 v25, v25
	v_and_b32_e32 v26, 0xffff0000, v38
	v_and_b32_e32 v27, 0xffff0000, v39
	global_load_dwordx2 v[38:39], v2, s[12:13]
	s_add_u32 s12, s12, 0x2000
	s_addc_u32 s13, s13, 0
	v_pk_mul_f32 v[8:9], v[8:9], v[24:25]
	v_pk_fma_f32 v[10:11], v[10:11], v[24:25], v[26:27]
	s_waitcnt vmcnt(31)
	v_lshlrev_b32_e32 v16, 16, v40
	v_lshlrev_b32_e32 v17, 16, v41
	v_exp_f32_e32 v16, v16
	v_exp_f32_e32 v17, v17
	v_and_b32_e32 v18, 0xffff0000, v40
	v_and_b32_e32 v19, 0xffff0000, v41
	global_load_dwordx2 v[40:41], v2, s[12:13]
	s_add_u32 s12, s12, 0x2000
	s_addc_u32 s13, s13, 0
	v_pk_mul_f32 v[8:9], v[8:9], v[16:17]
	v_pk_fma_f32 v[10:11], v[10:11], v[16:17], v[18:19]
	s_waitcnt vmcnt(31)
; __device__ __forceinline__ float bf_lo(unsigned w) { return __uint_as_float(w << 16); }
; __device__ __forceinline__ float bf_hi(unsigned w) { return __uint_as_float(w & 0xffff0000u); }
; __global__ void __launch_bounds__(NTHR, 2) hybrid_block_fwd(Args a) {
;     ...
;         for (int i = 0; i < CH_L; ++i) { const u32x2 q = pab[(size_t)i * (LW / 2)];
;             const f32x2 av = (f32x2){__builtin_amdgcn_exp2f(bf_lo(q.x)), __builtin_amdgcn_exp2f(bf_lo(q.y))}, bv = (f32x2){bf_hi(q.x), bf_hi(q.y)}; P = P * av; H = av * H + bv; }
	v_lshlrev_b32_e32 v24, 16, v42
	v_lshlrev_b32_e32 v25, 16, v43
	v_exp_f32_e32 v24, v24
	v_exp_f32_e32 v25, v25
	v_and_b32_e32 v26, 0xffff0000, v42
	v_and_b32_e32 v27, 0xffff0000, v43
	global_load_dwordx2 v[42:43], v2, s[12:13]
	s_add_u32 s12, s12, 0x2000
	s_addc_u32 s13, s13, 0
	v_pk_mul_f32 v[8:9], v[8:9], v[24:25]
	v_pk_fma_f32 v[10:11], v[10:11], v[24:25], v[26:27]
	s_waitcnt vmcnt(31)
	v_lshlrev_b32_e32 v16, 16, v44
	v_lshlrev_b32_e32 v17, 16, v45
	v_exp_f32_e32 v16, v16
	v_exp_f32_e32 v17, v17
	v_and_b32_e32 v18, 0xffff0000, v44
	v_and_b32_e32 v19, 0xffff0000, v45
	global_load_dwordx2 v[44:45], v2, s[12:13]
	s_add_u32 s12, s12, 0x2000
	s_addc_u32 s13, s13, 0
	v_pk_mul_f32 v[8:9], v[8:9], v[16:17]
	v_pk_fma_f32 v[10:11], v[10:11], v[16:17], v[18:19]
	s_waitcnt vmcnt(31)
	v_lshlrev_b32_e32 v24, 16, v46
	v_lshlrev_b32_e32 v25, 16, v47
	v_exp_f32_e32 v24, v24
	v_exp_f32_e32 v25, v25
	v_and_b32_e32 v26, 0xffff0000, v46
	v_and_b32_e32 v27, 0xffff0000, v47
	global_load_dwordx2 v[46:47], v2, s[12:13]
	s_add_u32 s12, s12, 0x2000
	s_addc_u32 s13, s13, 0
	v_pk_mul_f32 v[8:9], v[8:9], v[24:25]
	v_pk_fma_f32 v[10:11], v[10:11], v[24:25], v[26:27]
	s_waitcnt vmcnt(31)
	v_lshlrev_b32_e32 v16, 16, v48
	v_lshlrev_b32_e32 v17, 16, v49
	v_exp_f32_e32 v16, v16
	v_exp_f32_e32 v17, v17
	v_and_b32_e32 v18, 0xffff0000, v48
	v_and_b32_e32 v19, 0xffff0000, v49
	global_load_dwordx2 v[48:49], v2, s[12:13]
	s_add_u32 s12, s12, 0x2000
	s_addc_u32 s13, s13, 0
	v_pk_mul_f32 v[8:9], v[8:9], v[16:17]
	v_pk_fma_f32 v[10:11], v[10:11], v[16:17], v[18:19]
	s_waitcnt vmcnt(31)
	v_lshlrev_b32_e32 v24, 16, v50
	v_lshlrev_b32_e32 v25, 16, v51
	v_exp_f32_e32 v24, v24
	v_exp_f32_e32 v25, v25
	v_and_b32_e32 v26, 0xffff0000, v50
	v_and_b32_e32 v27, 0xffff0000, v51
	global_load_dwordx2 v[50:51], v2, s[12:13]
	s_add_u32 s12, s12, 0x2000
	s_addc_u32 s13, s13, 0
	v_pk_mul_f32 v[8:9], v[8:9], v[24:25]
	v_pk_fma_f32 v[10:11], v[10:11], v[24:25], v[26:27]
	s_waitcnt vmcnt(31)
	v_lshlrev_b32_e32 v16, 16, v52
	v_lshlrev_b32_e32 v17, 16, v53
	v_exp_f32_e32 v16, v16
	v_exp_f32_e32 v17, v17
	v_and_b32_e32 v18, 0xffff0000, v52
	v_and_b32_e32 v19, 0xffff0000, v53
	global_load_dwordx2 v[52:53], v2, s[12:13]
	s_add_u32 s12, s12, 0x2000
	s_addc_u32 s13, s13, 0
	v_pk_mul_f32 v[8:9], v[8:9], v[16:17]
	v_pk_fma_f32 v[10:11], v[10:11], v[16:17], v[18:19]
	s_waitcnt vmcnt(31)
	v_lshlrev_b32_e32 v24, 16, v54
	v_lshlrev_b32_e32 v25, 16, v55
	v_exp_f32_e32 v24, v24
	v_exp_f32_e32 v25, v25
	v_and_b32_e32 v26, 0xffff0000, v54
	v_and_b32_e32 v27, 0xffff0000, v55
	global_load_dwordx2 v[54:55], v2, s[12:13]
	s_add_u32 s12, s12, 0x2000
	s_addc_u32 s13, s13, 0
	v_pk_mul_f32 v[8:9], v[8:9], v[24:25]
	v_pk_fma_f32 v[10:11], v[10:11], v[24:25], v[26:27]
	s_waitcnt vmcnt(31)
	v_lshlrev_b32_e32 v16, 16, v56
	v_lshlrev_b32_e32 v17, 16, v57
	v_exp_f32_e32 v16, v16
	v_exp_f32_e32 v17, v17
	v_and_b32_e32 v18, 0xffff0000, v56
	v_and_b32_e32 v19, 0xffff0000, v57
	global_load_dwordx2 v[56:57], v2, s[12:13]
	s_add_u32 s12, s12, 0x2000
	s_addc_u32 s13, s13, 0
	v_pk_mul_f32 v[8:9], v[8:9], v[16:17]
	v_pk_fma_f32 v[10:11], v[10:11], v[16:17], v[18:19]
	s_waitcnt vmcnt(31)
	v_lshlrev_b32_e32 v24, 16, v58
	v_lshlrev_b32_e32 v25, 16, v59
	v_exp_f32_e32 v24, v24
	v_exp_f32_e32 v25, v25
	v_and_b32_e32 v26, 0xffff0000, v58
	v_and_b32_e32 v27, 0xffff0000, v59
	global_load_dwordx2 v[58:59], v2, s[12:13]
	s_add_u32 s12, s12, 0x2000
	s_addc_u32 s13, s13, 0
	v_pk_mul_f32 v[8:9], v[8:9], v[24:25]
	v_pk_fma_f32 v[10:11], v[10:11], v[24:25], v[26:27]
	s_waitcnt vmcnt(31)
	v_lshlrev_b32_e32 v16, 16, v60
	v_lshlrev_b32_e32 v17, 16, v61
	v_exp_f32_e32 v16, v16
	v_exp_f32_e32 v17, v17
	v_and_b32_e32 v18, 0xffff0000, v60
	v_and_b32_e32 v19, 0xffff0000, v61
	global_load_dwordx2 v[60:61], v2, s[12:13]
	s_add_u32 s12, s12, 0x2000
	s_addc_u32 s13, s13, 0
	v_pk_mul_f32 v[8:9], v[8:9], v[16:17]
	v_pk_fma_f32 v[10:11], v[10:11], v[16:17], v[18:19]
	s_waitcnt vmcnt(31)
	v_lshlrev_b32_e32 v24, 16, v62
	v_lshlrev_b32_e32 v25, 16, v63
	v_exp_f32_e32 v24, v24
	v_exp_f32_e32 v25, v25
	v_and_b32_e32 v26, 0xffff0000, v62
	v_and_b32_e32 v27, 0xffff0000, v63
	global_load_dwordx2 v[62:63], v2, s[12:13]
	s_add_u32 s12, s12, 0x2000
	s_addc_u32 s13, s13, 0
	v_pk_mul_f32 v[8:9], v[8:9], v[24:25]
	v_pk_fma_f32 v[10:11], v[10:11], v[24:25], v[26:27]
	s_waitcnt vmcnt(31)
	v_lshlrev_b32_e32 v16, 16, v64
	v_lshlrev_b32_e32 v17, 16, v65
	v_exp_f32_e32 v16, v16
	v_exp_f32_e32 v17, v17
	v_and_b32_e32 v18, 0xffff0000, v64
	v_and_b32_e32 v19, 0xffff0000, v65
	global_load_dwordx2 v[64:65], v2, s[12:13]
	s_add_u32 s12, s12, 0x2000
	s_addc_u32 s13, s13, 0
	v_pk_mul_f32 v[8:9], v[8:9], v[16:17]
	v_pk_fma_f32 v[10:11], v[10:11], v[16:17], v[18:19]
	s_waitcnt vmcnt(31)
	v_lshlrev_b32_e32 v24, 16, v66
	v_lshlrev_b32_e32 v25, 16, v67
	v_exp_f32_e32 v24, v24
	v_exp_f32_e32 v25, v25
	v_and_b32_e32 v26, 0xffff0000, v66
	v_and_b32_e32 v27, 0xffff0000, v67
	global_load_dwordx2 v[66:67], v2, s[12:13]
	s_add_u32 s12, s12, 0x2000
	s_addc_u32 s13, s13, 0
	v_pk_mul_f32 v[8:9], v[8:9], v[24:25]
	v_pk_fma_f32 v[10:11], v[10:11], v[24:25], v[26:27]
	s_waitcnt vmcnt(31)
	v_lshlrev_b32_e32 v16, 16, v68
	v_lshlrev_b32_e32 v17, 16, v69
	v_exp_f32_e32 v16, v16
	v_exp_f32_e32 v17, v17
	v_and_b32_e32 v18, 0xffff0000, v68
	v_and_b32_e32 v19, 0xffff0000, v69
	global_load_dwordx2 v[68:69], v2, s[12:13]
	s_add_u32 s12, s12, 0x2000
	s_addc_u32 s13, s13, 0
	v_pk_mul_f32 v[8:9], v[8:9], v[16:17]
	v_pk_fma_f32 v[10:11], v[10:11], v[16:17], v[18:19]
	s_waitcnt vmcnt(31)
; __device__ __forceinline__ float bf_lo(unsigned w) { return __uint_as_float(w << 16); }
; __device__ __forceinline__ float bf_hi(unsigned w) { return __uint_as_float(w & 0xffff0000u); }
; __global__ void __launch_bounds__(NTHR, 2) hybrid_block_fwd(Args a) {
;     ...
;         for (int i = 0; i < CH_L; ++i) { const u32x2 q = pab[(size_t)i * (LW / 2)];
;             const f32x2 av = (f32x2){__builtin_amdgcn_exp2f(bf_lo(q.x)), __builtin_amdgcn_exp2f(bf_lo(q.y))}, bv = (f32x2){bf_hi(q.x), bf_hi(q.y)}; P = P * av; H = av * H + bv; }
	v_lshlrev_b32_e32 v24, 16, v70
	v_lshlrev_b32_e32 v25, 16, v71
	v_exp_f32_e32 v24, v24
	v_exp_f32_e32 v25, v25
	v_and_b32_e32 v26, 0xffff0000, v70
	v_and_b32_e32 v27, 0xffff0000, v71
	global_load_dwordx2 v[70:71], v2, s[12:13]
	s_add_u32 s12, s12, 0x2000
	s_addc_u32 s13, s13, 0
	v_pk_mul_f32 v[8:9], v[8:9], v[24:25]
	v_pk_fma_f32 v[10:11], v[10:11], v[24:25], v[26:27]
	s_waitcnt vmcnt(31)
	v_lshlrev_b32_e32 v16, 16, v72
	v_lshlrev_b32_e32 v17, 16, v73
	v_exp_f32_e32 v16, v16
	v_exp_f32_e32 v17, v17
	v_and_b32_e32 v18, 0xffff0000, v72
	v_and_b32_e32 v19, 0xffff0000, v73
	global_load_dwordx2 v[72:73], v2, s[12:13]
	s_add_u32 s12, s12, 0x2000
	s_addc_u32 s13, s13, 0
	v_pk_mul_f32 v[8:9], v[8:9], v[16:17]
	v_pk_fma_f32 v[10:11], v[10:11], v[16:17], v[18:19]
	s_waitcnt vmcnt(31)
	v_lshlrev_b32_e32 v24, 16, v74
	v_lshlrev_b32_e32 v25, 16, v75
	v_exp_f32_e32 v24, v24
	v_exp_f32_e32 v25, v25
	v_and_b32_e32 v26, 0xffff0000, v74
	v_and_b32_e32 v27, 0xffff0000, v75
	global_load_dwordx2 v[74:75], v2, s[12:13]
	s_add_u32 s12, s12, 0x2000
	s_addc_u32 s13, s13, 0
	v_pk_mul_f32 v[8:9], v[8:9], v[24:25]
	v_pk_fma_f32 v[10:11], v[10:11], v[24:25], v[26:27]
	s_waitcnt vmcnt(31)
	v_lshlrev_b32_e32 v16, 16, v76
	v_lshlrev_b32_e32 v17, 16, v77
	v_exp_f32_e32 v16, v16
	v_exp_f32_e32 v17, v17
	v_and_b32_e32 v18, 0xffff0000, v76
	v_and_b32_e32 v19, 0xffff0000, v77
	global_load_dwordx2 v[76:77], v2, s[12:13]
	s_add_u32 s12, s12, 0x2000
	s_addc_u32 s13, s13, 0
	v_pk_mul_f32 v[8:9], v[8:9], v[16:17]
	v_pk_fma_f32 v[10:11], v[10:11], v[16:17], v[18:19]
	s_waitcnt vmcnt(31)
	v_lshlrev_b32_e32 v24, 16, v78
	v_lshlrev_b32_e32 v25, 16, v79
	v_exp_f32_e32 v24, v24
	v_exp_f32_e32 v25, v25
	v_and_b32_e32 v26, 0xffff0000, v78
	v_and_b32_e32 v27, 0xffff0000, v79
	global_load_dwordx2 v[78:79], v2, s[12:13]
	s_add_u32 s12, s12, 0x2000
	s_addc_u32 s13, s13, 0
	v_pk_mul_f32 v[8:9], v[8:9], v[24:25]
	v_pk_fma_f32 v[10:11], v[10:11], v[24:25], v[26:27]
	s_waitcnt vmcnt(31)
	v_lshlrev_b32_e32 v16, 16, v80
	v_lshlrev_b32_e32 v17, 16, v81
	v_exp_f32_e32 v16, v16
	v_exp_f32_e32 v17, v17
	v_and_b32_e32 v18, 0xffff0000, v80
	v_and_b32_e32 v19, 0xffff0000, v81
	global_load_dwordx2 v[80:81], v2, s[12:13]
	s_add_u32 s12, s12, 0x2000
	s_addc_u32 s13, s13, 0
	v_pk_mul_f32 v[8:9], v[8:9], v[16:17]
	v_pk_fma_f32 v[10:11], v[10:11], v[16:17], v[18:19]
	s_waitcnt vmcnt(31)
	v_lshlrev_b32_e32 v24, 16, v82
	v_lshlrev_b32_e32 v25, 16, v83
	v_exp_f32_e32 v24, v24
	v_exp_f32_e32 v25, v25
	v_and_b32_e32 v26, 0xffff0000, v82
	v_and_b32_e32 v27, 0xffff0000, v83
	global_load_dwordx2 v[82:83], v2, s[12:13]
	s_add_u32 s12, s12, 0x2000
	s_addc_u32 s13, s13, 0
	v_pk_mul_f32 v[8:9], v[8:9], v[24:25]
	v_pk_fma_f32 v[10:11], v[10:11], v[24:25], v[26:27]
	s_waitcnt vmcnt(31)
	v_lshlrev_b32_e32 v16, 16, v84
	v_lshlrev_b32_e32 v17, 16, v85
	v_exp_f32_e32 v16, v16
	v_exp_f32_e32 v17, v17
	v_and_b32_e32 v18, 0xffff0000, v84
	v_and_b32_e32 v19, 0xffff0000, v85
	global_load_dwordx2 v[84:85], v2, s[12:13]
	s_add_u32 s12, s12, 0x2000
	s_addc_u32 s13, s13, 0
	v_pk_mul_f32 v[8:9], v[8:9], v[16:17]
	v_pk_fma_f32 v[10:11], v[10:11], v[16:17], v[18:19]
	s_waitcnt vmcnt(31)
	v_lshlrev_b32_e32 v24, 16, v86
	v_lshlrev_b32_e32 v25, 16, v87
	v_exp_f32_e32 v24, v24
	v_exp_f32_e32 v25, v25
	v_and_b32_e32 v26, 0xffff0000, v86
	v_and_b32_e32 v27, 0xffff0000, v87
	global_load_dwordx2 v[86:87], v2, s[12:13]
	s_add_u32 s12, s12, 0x2000
	s_addc_u32 s13, s13, 0
	v_pk_mul_f32 v[8:9], v[8:9], v[24:25]
	v_pk_fma_f32 v[10:11], v[10:11], v[24:25], v[26:27]
	s_waitcnt vmcnt(31)
	v_lshlrev_b32_e32 v16, 16, v88
	v_lshlrev_b32_e32 v17, 16, v89
	v_exp_f32_e32 v16, v16
	v_exp_f32_e32 v17, v17
	v_and_b32_e32 v18, 0xffff0000, v88
	v_and_b32_e32 v19, 0xffff0000, v89
	global_load_dwordx2 v[88:89], v2, s[12:13]
	s_add_u32 s12, s12, 0x2000
	s_addc_u32 s13, s13, 0
	v_pk_mul_f32 v[8:9], v[8:9], v[16:17]
	v_pk_fma_f32 v[10:11], v[10:11], v[16:17], v[18:19]
	s_waitcnt vmcnt(31)
	v_lshlrev_b32_e32 v24, 16, v90
	v_lshlrev_b32_e32 v25, 16, v91
	v_exp_f32_e32 v24, v24
	v_exp_f32_e32 v25, v25
	v_and_b32_e32 v26, 0xffff0000, v90
	v_and_b32_e32 v27, 0xffff0000, v91
	global_load_dwordx2 v[90:91], v2, s[12:13]
	s_add_u32 s12, s12, 0x2000
	s_addc_u32 s13, s13, 0
	v_pk_mul_f32 v[8:9], v[8:9], v[24:25]
	v_pk_fma_f32 v[10:11], v[10:11], v[24:25], v[26:27]
	s_waitcnt vmcnt(31)
	v_lshlrev_b32_e32 v16, 16, v92
	v_lshlrev_b32_e32 v17, 16, v93
	v_exp_f32_e32 v16, v16
	v_exp_f32_e32 v17, v17
	v_and_b32_e32 v18, 0xffff0000, v92
	v_and_b32_e32 v19, 0xffff0000, v93
	global_load_dwordx2 v[92:93], v2, s[12:13]
	s_add_u32 s12, s12, 0x2000
	s_addc_u32 s13, s13, 0
	v_pk_mul_f32 v[8:9], v[8:9], v[16:17]
	v_pk_fma_f32 v[10:11], v[10:11], v[16:17], v[18:19]
	s_waitcnt vmcnt(31)
	v_lshlrev_b32_e32 v24, 16, v94
	v_lshlrev_b32_e32 v25, 16, v95
	v_exp_f32_e32 v24, v24
	v_exp_f32_e32 v25, v25
	v_and_b32_e32 v26, 0xffff0000, v94
	v_and_b32_e32 v27, 0xffff0000, v95
	global_load_dwordx2 v[94:95], v2, s[12:13]
	s_add_u32 s12, s12, 0x2000
	s_addc_u32 s13, s13, 0
	v_pk_mul_f32 v[8:9], v[8:9], v[24:25]
	v_pk_fma_f32 v[10:11], v[10:11], v[24:25], v[26:27]
	s_sub_u32 s8, s8, 1
	s_cmp_lg_u32 s8, 0
	s_cbranch_scc1 .Lp2c_steady
; __device__ __forceinline__ float bf_lo(unsigned w) { return __uint_as_float(w << 16); }
; __device__ __forceinline__ float bf_hi(unsigned w) { return __uint_as_float(w & 0xffff0000u); }
; __global__ void __launch_bounds__(NTHR, 2) hybrid_block_fwd(Args a) {
;     ...
;         for (int i = 0; i < CH_L; ++i) { const u32x2 q = pab[(size_t)i * (LW / 2)];
;             const f32x2 av = (f32x2){__builtin_amdgcn_exp2f(bf_lo(q.x)), __builtin_amdgcn_exp2f(bf_lo(q.y))}, bv = (f32x2){bf_hi(q.x), bf_hi(q.y)}; P = P * av; H = av * H + bv; }
	s_waitcnt vmcnt(31)
	v_lshlrev_b32_e32 v16, 16, v32
	v_lshlrev_b32_e32 v17, 16, v33
	v_exp_f32_e32 v16, v16
	v_exp_f32_e32 v17, v17
	v_and_b32_e32 v18, 0xffff0000, v32
	v_and_b32_e32 v19, 0xffff0000, v33
	v_pk_mul_f32 v[8:9], v[8:9], v[16:17]
	v_pk_fma_f32 v[10:11], v[10:11], v[16:17], v[18:19]
	s_waitcnt vmcnt(30)
	v_lshlrev_b32_e32 v24, 16, v34
	v_lshlrev_b32_e32 v25, 16, v35
	v_exp_f32_e32 v24, v24
	v_exp_f32_e32 v25, v25
	v_and_b32_e32 v26, 0xffff0000, v34
	v_and_b32_e32 v27, 0xffff0000, v35
	v_pk_mul_f32 v[8:9], v[8:9], v[24:25]
	v_pk_fma_f32 v[10:11], v[10:11], v[24:25], v[26:27]
	s_waitcnt vmcnt(29)
	v_lshlrev_b32_e32 v16, 16, v36
	v_lshlrev_b32_e32 v17, 16, v37
	v_exp_f32_e32 v16, v16
	v_exp_f32_e32 v17, v17
	v_and_b32_e32 v18, 0xffff0000, v36
	v_and_b32_e32 v19, 0xffff0000, v37
	v_pk_mul_f32 v[8:9], v[8:9], v[16:17]
	v_pk_fma_f32 v[10:11], v[10:11], v[16:17], v[18:19]
	s_waitcnt vmcnt(28)
	v_lshlrev_b32_e32 v24, 16, v38
	v_lshlrev_b32_e32 v25, 16, v39
	v_exp_f32_e32 v24, v24
	v_exp_f32_e32 v25, v25
	v_and_b32_e32 v26, 0xffff0000, v38
	v_and_b32_e32 v27, 0xffff0000, v39
	v_pk_mul_f32 v[8:9], v[8:9], v[24:25]
	v_pk_fma_f32 v[10:11], v[10:11], v[24:25], v[26:27]
	s_waitcnt vmcnt(27)
	v_lshlrev_b32_e32 v16, 16, v40
	v_lshlrev_b32_e32 v17, 16, v41
	v_exp_f32_e32 v16, v16
	v_exp_f32_e32 v17, v17
	v_and_b32_e32 v18, 0xffff0000, v40
	v_and_b32_e32 v19, 0xffff0000, v41
	v_pk_mul_f32 v[8:9], v[8:9], v[16:17]
	v_pk_fma_f32 v[10:11], v[10:11], v[16:17], v[18:19]
	s_waitcnt vmcnt(26)
	v_lshlrev_b32_e32 v24, 16, v42
	v_lshlrev_b32_e32 v25, 16, v43
	v_exp_f32_e32 v24, v24
	v_exp_f32_e32 v25, v25
	v_and_b32_e32 v26, 0xffff0000, v42
	v_and_b32_e32 v27, 0xffff0000, v43
	v_pk_mul_f32 v[8:9], v[8:9], v[24:25]
	v_pk_fma_f32 v[10:11], v[10:11], v[24:25], v[26:27]
	s_waitcnt vmcnt(25)
	v_lshlrev_b32_e32 v16, 16, v44
	v_lshlrev_b32_e32 v17, 16, v45
	v_exp_f32_e32 v16, v16
	v_exp_f32_e32 v17, v17
	v_and_b32_e32 v18, 0xffff0000, v44
	v_and_b32_e32 v19, 0xffff0000, v45
	v_pk_mul_f32 v[8:9], v[8:9], v[16:17]
	v_pk_fma_f32 v[10:11], v[10:11], v[16:17], v[18:19]
	s_waitcnt vmcnt(24)
	v_lshlrev_b32_e32 v24, 16, v46
	v_lshlrev_b32_e32 v25, 16, v47
	v_exp_f32_e32 v24, v24
	v_exp_f32_e32 v25, v25
	v_and_b32_e32 v26, 0xffff0000, v46
	v_and_b32_e32 v27, 0xffff0000, v47
	v_pk_mul_f32 v[8:9], v[8:9], v[24:25]
	v_pk_fma_f32 v[10:11], v[10:11], v[24:25], v[26:27]
	s_waitcnt vmcnt(23)
	v_lshlrev_b32_e32 v16, 16, v48
	v_lshlrev_b32_e32 v17, 16, v49
	v_exp_f32_e32 v16, v16
	v_exp_f32_e32 v17, v17
	v_and_b32_e32 v18, 0xffff0000, v48
	v_and_b32_e32 v19, 0xffff0000, v49
	v_pk_mul_f32 v[8:9], v[8:9], v[16:17]
	v_pk_fma_f32 v[10:11], v[10:11], v[16:17], v[18:19]
	s_waitcnt vmcnt(22)
	v_lshlrev_b32_e32 v24, 16, v50
	v_lshlrev_b32_e32 v25, 16, v51
	v_exp_f32_e32 v24, v24
	v_exp_f32_e32 v25, v25
	v_and_b32_e32 v26, 0xffff0000, v50
	v_and_b32_e32 v27, 0xffff0000, v51
	v_pk_mul_f32 v[8:9], v[8:9], v[24:25]
	v_pk_fma_f32 v[10:11], v[10:11], v[24:25], v[26:27]
	s_waitcnt vmcnt(21)
	v_lshlrev_b32_e32 v16, 16, v52
	v_lshlrev_b32_e32 v17, 16, v53
	v_exp_f32_e32 v16, v16
	v_exp_f32_e32 v17, v17
	v_and_b32_e32 v18, 0xffff0000, v52
	v_and_b32_e32 v19, 0xffff0000, v53
	v_pk_mul_f32 v[8:9], v[8:9], v[16:17]
	v_pk_fma_f32 v[10:11], v[10:11], v[16:17], v[18:19]
	s_waitcnt vmcnt(20)
	v_lshlrev_b32_e32 v24, 16, v54
	v_lshlrev_b32_e32 v25, 16, v55
	v_exp_f32_e32 v24, v24
	v_exp_f32_e32 v25, v25
	v_and_b32_e32 v26, 0xffff0000, v54
	v_and_b32_e32 v27, 0xffff0000, v55
	v_pk_mul_f32 v[8:9], v[8:9], v[24:25]
	v_pk_fma_f32 v[10:11], v[10:11], v[24:25], v[26:27]
	s_waitcnt vmcnt(19)
	v_lshlrev_b32_e32 v16, 16, v56
	v_lshlrev_b32_e32 v17, 16, v57
	v_exp_f32_e32 v16, v16
	v_exp_f32_e32 v17, v17
	v_and_b32_e32 v18, 0xffff0000, v56
	v_and_b32_e32 v19, 0xffff0000, v57
	v_pk_mul_f32 v[8:9], v[8:9], v[16:17]
	v_pk_fma_f32 v[10:11], v[10:11], v[16:17], v[18:19]
	s_waitcnt vmcnt(18)
	v_lshlrev_b32_e32 v24, 16, v58
	v_lshlrev_b32_e32 v25, 16, v59
	v_exp_f32_e32 v24, v24
	v_exp_f32_e32 v25, v25
	v_and_b32_e32 v26, 0xffff0000, v58
	v_and_b32_e32 v27, 0xffff0000, v59
	v_pk_mul_f32 v[8:9], v[8:9], v[24:25]
	v_pk_fma_f32 v[10:11], v[10:11], v[24:25], v[26:27]
	s_waitcnt vmcnt(17)
	v_lshlrev_b32_e32 v16, 16, v60
	v_lshlrev_b32_e32 v17, 16, v61
	v_exp_f32_e32 v16, v16
	v_exp_f32_e32 v17, v17
	v_and_b32_e32 v18, 0xffff0000, v60
	v_and_b32_e32 v19, 0xffff0000, v61
	v_pk_mul_f32 v[8:9], v[8:9], v[16:17]
	v_pk_fma_f32 v[10:11], v[10:11], v[16:17], v[18:19]
	s_waitcnt vmcnt(16)
	v_lshlrev_b32_e32 v24, 16, v62
	v_lshlrev_b32_e32 v25, 16, v63
	v_exp_f32_e32 v24, v24
	v_exp_f32_e32 v25, v25
	v_and_b32_e32 v26, 0xffff0000, v62
	v_and_b32_e32 v27, 0xffff0000, v63
	v_pk_mul_f32 v[8:9], v[8:9], v[24:25]
	v_pk_fma_f32 v[10:11], v[10:11], v[24:25], v[26:27]
	s_waitcnt vmcnt(15)
	v_lshlrev_b32_e32 v16, 16, v64
	v_lshlrev_b32_e32 v17, 16, v65
	v_exp_f32_e32 v16, v16
	v_exp_f32_e32 v17, v17
	v_and_b32_e32 v18, 0xffff0000, v64
	v_and_b32_e32 v19, 0xffff0000, v65
	v_pk_mul_f32 v[8:9], v[8:9], v[16:17]
	v_pk_fma_f32 v[10:11], v[10:11], v[16:17], v[18:19]
	s_waitcnt vmcnt(14)
	v_lshlrev_b32_e32 v24, 16, v66
	v_lshlrev_b32_e32 v25, 16, v67
	v_exp_f32_e32 v24, v24
	v_exp_f32_e32 v25, v25
	v_and_b32_e32 v26, 0xffff0000, v66
	v_and_b32_e32 v27, 0xffff0000, v67
	v_pk_mul_f32 v[8:9], v[8:9], v[24:25]
	v_pk_fma_f32 v[10:11], v[10:11], v[24:25], v[26:27]
	s_waitcnt vmcnt(13)
	v_lshlrev_b32_e32 v16, 16, v68
	v_lshlrev_b32_e32 v17, 16, v69
	v_exp_f32_e32 v16, v16
	v_exp_f32_e32 v17, v17
	v_and_b32_e32 v18, 0xffff0000, v68
	v_and_b32_e32 v19, 0xffff0000, v69
	v_pk_mul_f32 v[8:9], v[8:9], v[16:17]
	v_pk_fma_f32 v[10:11], v[10:11], v[16:17], v[18:19]
	s_waitcnt vmcnt(12)
; __device__ __forceinline__ float bf_lo(unsigned w) { return __uint_as_float(w << 16); }
; __device__ __forceinline__ float bf_hi(unsigned w) { return __uint_as_float(w & 0xffff0000u); }
; __device__ __forceinline__ void xcd_barrier(const XcdBarrier& b) {
;     asm volatile("s_waitcnt vmcnt(0)" ::: "memory");
;     __syncthreads();
;     if (threadIdx.x == 0) {
;         unsigned* bar = b.bar;
;         __builtin_amdgcn_s_waitcnt(0);
;         unsigned nloc = b.st[0], nx = b.st[1];
;         if (nloc == 0u) { xcd_barrier_complete(bar, b.x, nloc, nx); b.st[0] = nloc; b.st[1] = nx; }
; __global__ void __launch_bounds__(NTHR, 2) hybrid_block_fwd(Args a) {
;     ...
;         for (int i = 0; i < CH_L; ++i) { const u32x2 q = pab[(size_t)i * (LW / 2)];
;             const f32x2 av = (f32x2){__builtin_amdgcn_exp2f(bf_lo(q.x)), __builtin_amdgcn_exp2f(bf_lo(q.y))}, bv = (f32x2){bf_hi(q.x), bf_hi(q.y)}; P = P * av; H = av * H + bv; }
;         ((f32x2*)(AGGP + (size_t)(b * NCH + chunk) * LW))[c2] = P; ((f32x2*)(AGGH + (size_t)(b * NCH + chunk) * LW))[c2] = H;
	v_lshlrev_b32_e32 v24, 16, v70
	v_lshlrev_b32_e32 v25, 16, v71
	v_exp_f32_e32 v24, v24
	v_exp_f32_e32 v25, v25
	v_and_b32_e32 v26, 0xffff0000, v70
	v_and_b32_e32 v27, 0xffff0000, v71
	v_pk_mul_f32 v[8:9], v[8:9], v[24:25]
	v_pk_fma_f32 v[10:11], v[10:11], v[24:25], v[26:27]
	s_waitcnt vmcnt(11)
	v_lshlrev_b32_e32 v16, 16, v72
	v_lshlrev_b32_e32 v17, 16, v73
	v_exp_f32_e32 v16, v16
	v_exp_f32_e32 v17, v17
	v_and_b32_e32 v18, 0xffff0000, v72
	v_and_b32_e32 v19, 0xffff0000, v73
	v_pk_mul_f32 v[8:9], v[8:9], v[16:17]
	v_pk_fma_f32 v[10:11], v[10:11], v[16:17], v[18:19]
	s_waitcnt vmcnt(10)
	v_lshlrev_b32_e32 v24, 16, v74
	v_lshlrev_b32_e32 v25, 16, v75
	v_exp_f32_e32 v24, v24
	v_exp_f32_e32 v25, v25
	v_and_b32_e32 v26, 0xffff0000, v74
	v_and_b32_e32 v27, 0xffff0000, v75
	v_pk_mul_f32 v[8:9], v[8:9], v[24:25]
	v_pk_fma_f32 v[10:11], v[10:11], v[24:25], v[26:27]
	s_waitcnt vmcnt(9)
	v_lshlrev_b32_e32 v16, 16, v76
	v_lshlrev_b32_e32 v17, 16, v77
	v_exp_f32_e32 v16, v16
	v_exp_f32_e32 v17, v17
	v_and_b32_e32 v18, 0xffff0000, v76
	v_and_b32_e32 v19, 0xffff0000, v77
	v_pk_mul_f32 v[8:9], v[8:9], v[16:17]
	v_pk_fma_f32 v[10:11], v[10:11], v[16:17], v[18:19]
	s_waitcnt vmcnt(8)
	v_lshlrev_b32_e32 v24, 16, v78
	v_lshlrev_b32_e32 v25, 16, v79
	v_exp_f32_e32 v24, v24
	v_exp_f32_e32 v25, v25
	v_and_b32_e32 v26, 0xffff0000, v78
	v_and_b32_e32 v27, 0xffff0000, v79
	v_pk_mul_f32 v[8:9], v[8:9], v[24:25]
	v_pk_fma_f32 v[10:11], v[10:11], v[24:25], v[26:27]
	s_waitcnt vmcnt(7)
	v_lshlrev_b32_e32 v16, 16, v80
	v_lshlrev_b32_e32 v17, 16, v81
	v_exp_f32_e32 v16, v16
	v_exp_f32_e32 v17, v17
	v_and_b32_e32 v18, 0xffff0000, v80
	v_and_b32_e32 v19, 0xffff0000, v81
	v_pk_mul_f32 v[8:9], v[8:9], v[16:17]
	v_pk_fma_f32 v[10:11], v[10:11], v[16:17], v[18:19]
	s_waitcnt vmcnt(6)
	v_lshlrev_b32_e32 v24, 16, v82
	v_lshlrev_b32_e32 v25, 16, v83
	v_exp_f32_e32 v24, v24
	v_exp_f32_e32 v25, v25
	v_and_b32_e32 v26, 0xffff0000, v82
	v_and_b32_e32 v27, 0xffff0000, v83
	v_pk_mul_f32 v[8:9], v[8:9], v[24:25]
	v_pk_fma_f32 v[10:11], v[10:11], v[24:25], v[26:27]
	s_waitcnt vmcnt(5)
	v_lshlrev_b32_e32 v16, 16, v84
	v_lshlrev_b32_e32 v17, 16, v85
	v_exp_f32_e32 v16, v16
	v_exp_f32_e32 v17, v17
	v_and_b32_e32 v18, 0xffff0000, v84
	v_and_b32_e32 v19, 0xffff0000, v85
	v_pk_mul_f32 v[8:9], v[8:9], v[16:17]
	v_pk_fma_f32 v[10:11], v[10:11], v[16:17], v[18:19]
	s_waitcnt vmcnt(4)
	v_lshlrev_b32_e32 v24, 16, v86
	v_lshlrev_b32_e32 v25, 16, v87
	v_exp_f32_e32 v24, v24
	v_exp_f32_e32 v25, v25
	v_and_b32_e32 v26, 0xffff0000, v86
	v_and_b32_e32 v27, 0xffff0000, v87
	v_pk_mul_f32 v[8:9], v[8:9], v[24:25]
	v_pk_fma_f32 v[10:11], v[10:11], v[24:25], v[26:27]
	s_waitcnt vmcnt(3)
	v_lshlrev_b32_e32 v16, 16, v88
	v_lshlrev_b32_e32 v17, 16, v89
	v_exp_f32_e32 v16, v16
	v_exp_f32_e32 v17, v17
	v_and_b32_e32 v18, 0xffff0000, v88
	v_and_b32_e32 v19, 0xffff0000, v89
	v_pk_mul_f32 v[8:9], v[8:9], v[16:17]
	v_pk_fma_f32 v[10:11], v[10:11], v[16:17], v[18:19]
	s_waitcnt vmcnt(2)
	v_lshlrev_b32_e32 v24, 16, v90
	v_lshlrev_b32_e32 v25, 16, v91
	v_exp_f32_e32 v24, v24
	v_exp_f32_e32 v25, v25
	v_and_b32_e32 v26, 0xffff0000, v90
	v_and_b32_e32 v27, 0xffff0000, v91
	v_pk_mul_f32 v[8:9], v[8:9], v[24:25]
	v_pk_fma_f32 v[10:11], v[10:11], v[24:25], v[26:27]
	s_waitcnt vmcnt(1)
	v_lshlrev_b32_e32 v16, 16, v92
	v_lshlrev_b32_e32 v17, 16, v93
	v_exp_f32_e32 v16, v16
	v_exp_f32_e32 v17, v17
	v_and_b32_e32 v18, 0xffff0000, v92
	v_and_b32_e32 v19, 0xffff0000, v93
	v_pk_mul_f32 v[8:9], v[8:9], v[16:17]
	v_pk_fma_f32 v[10:11], v[10:11], v[16:17], v[18:19]
	s_waitcnt vmcnt(0)
	v_lshlrev_b32_e32 v24, 16, v94
	v_lshlrev_b32_e32 v25, 16, v95
	v_exp_f32_e32 v24, v24
	v_exp_f32_e32 v25, v25
	v_and_b32_e32 v26, 0xffff0000, v94
	v_and_b32_e32 v27, 0xffff0000, v95
	v_pk_mul_f32 v[8:9], v[8:9], v[24:25]
	v_pk_fma_f32 v[10:11], v[10:11], v[24:25], v[26:27]
	s_lshl_b32 s10, s9, 13
	s_add_u32 s0, s94, s10
	s_addc_u32 s1, s95, 0
	s_add_u32 s0, s0, 0x100000
	s_addc_u32 s1, s1, 0
	global_store_dwordx2 v2, v[8:9], s[0:1]
	global_store_dwordx2 v6, v[10:11], s[0:1]
	s_add_u32 s0, s94, 0x100000
	s_addc_u32 s1, s95, 0
	s_add_u32 s4, s94, 0x200000
	s_addc_u32 s5, s95, 0
	s_waitcnt vmcnt(0)
	s_barrier
	s_mov_b64 s[8:9], exec
	v_readlane_b32 s10, v248, 6
	v_readlane_b32 s11, v248, 7
	s_and_b64 s[10:11], s[8:9], s[10:11]
	s_xor_b64 s[8:9], s[10:11], s[8:9]
	s_mov_b64 exec, s[10:11]
	s_cbranch_execz .LBB0_669
	s_add_i32 s10, 0, 0x20020
	v_mov_b32_e32 v0, s10
	s_waitcnt vmcnt(0) expcnt(0) lgkmcnt(0)
	ds_read_b32 v2, v0
	s_add_i32 s10, 0, 0x20024
	v_mov_b32_e32 v0, s10
	ds_read_b32 v0, v0
	s_waitcnt lgkmcnt(1)
	v_cmp_ne_u32_e32 vcc, 0, v2
	s_cbranch_vccnz .LBB0_632
	v_readlane_b32 s10, v248, 2
	v_readlane_b32 s11, v248, 3
	v_readlane_b32 s12, v248, 1
	s_mul_i32 s18, s11, s12
	s_mul_i32 s18, s18, s10
	s_add_u32 s10, s94, 0x40200
	s_addc_u32 s11, s95, 0
	s_add_u32 s38, s94, 0x40400
	s_addc_u32 s39, s95, 0
	s_add_u32 s42, s94, 0x40500
	s_addc_u32 s43, s95, 0
	s_add_u32 s54, s94, 0x40600
	s_addc_u32 s55, s95, 0
	s_add_u32 s56, s94, 0x40700
	s_addc_u32 s57, s95, 0
	s_add_u32 s58, s94, 0x40800
	s_addc_u32 s59, s95, 0
	s_add_u32 s60, s94, 0x40900
	s_addc_u32 s61, s95, 0
	s_add_u32 s62, s94, 0x40a00
	s_addc_u32 s63, s95, 0
	s_add_u32 s64, s94, 0x40b00
	s_addc_u32 s65, s95, 0
	s_add_u32 s66, s94, 0x40c00
	s_addc_u32 s67, s95, 0
	s_add_u32 s70, s94, 0x40d00
	s_addc_u32 s71, s95, 0
	s_add_u32 s72, s94, 0x40e00
	s_addc_u32 s73, s95, 0
	s_add_u32 s74, s94, 0x40f00
	s_addc_u32 s75, s95, 0
	s_add_u32 s76, s94, 0x41000
	s_addc_u32 s77, s95, 0
	s_add_u32 s78, s94, 0x41100
	s_addc_u32 s79, s95, 0
	s_add_u32 s34, s94, 0x41200
	s_addc_u32 s35, s95, 0
	s_add_u32 s48, s94, 0x41300
	s_addc_u32 s49, s95, 0
	s_mov_b32 s19, 1
	v_mov_b32_e32 v16, 0
	s_branch .LBB0_620
